# k59: k58 + nt on the output-projection epilogue's streaming residual (x) loads
# baseline (speedup 1.0000x reference)
;     __device__ __forceinline__ void operator()(const f32x4 (&acc)[2][2][4][2], const pg8::Unit& u, int wr, int wc, int fr, int fq) const {
;         const int row0 = u.pm * 256 + wr * 64 + fr, col0 = u.pn * 256 + wc * 32 + fq * 4;
;         const float* gt = mod + (size_t)(row0 >> 13) * 3072 + 2048 + col0;
;         f32x4 gv[2][2];
; #pragma unroll
;         for (int bj = 0; bj < 2; ++bj)
; #pragma unroll
;             for (int n = 0; n < 2; ++n) gv[bj][n] = *(const f32x4*)(gt + bj * 128 + 16 * n);
; #pragma unroll
;         for (int ai = 0; ai < 2; ++ai)
; #pragma unroll
;             for (int mp = 0; mp < 2; ++mp) {
;                 f32x4 xv[2][2][2];
; #pragma unroll
;                 for (int mm = 0; mm < 2; ++mm) { const float* xr = xp + (size_t)(row0 + ai * 128 + (2 * mp + mm) * 16) * DM + col0;
; #pragma unroll
;                     for (int bj = 0; bj < 2; ++bj)
; #pragma unroll
;                         for (int n = 0; n < 2; ++n) xv[mm][bj][n] = *(const f32x4*)(xr + bj * 128 + 16 * n); }
;                 asm volatile("" ::: "memory");
; #pragma unroll
;                 for (int mm = 0; mm < 2; ++mm) { float* yr = yp + (size_t)(row0 + ai * 128 + (2 * mp + mm) * 16) * DM + col0;
; #pragma unroll
;                     for (int bj = 0; bj < 2; ++bj)
; #pragma unroll
;                         for (int n = 0; n < 2; ++n) { const f32x4 yv = xv[mm][bj][n] + gv[bj][n] * acc[ai][bj][2 * mp + mm][n]; const float* yp_ = yr + bj * 128 + 16 * n;
;                             asm volatile("global_store_dwordx4 %0, %1, off sc1" :: "v"(yp_), "v"(yv) : "memory"); } }
.LBB0_1050:
	s_lshl_b32 s25, s34, 8
	s_add_i32 s25, s25, s51
	s_ashr_i32 s27, s25, 13
	s_mul_i32 s38, s27, 0xc00
	s_ashr_i32 s39, s38, 31
	v_lshl_or_b32 v128, s57, 8, v164
	s_lshl_b64 s[38:39], s[38:39], 2
	s_add_u32 s38, s92, s38
	v_ashrrev_i32_e32 v129, 31, v128
	v_or_b32_e32 v200, s25, v162
	s_addc_u32 s39, s93, s39
	v_lshlrev_b64 v[156:157], 2, v[128:129]
	v_ashrrev_i32_e32 v201, 31, v200
	v_lshl_add_u64 v[136:137], s[38:39], 0, v[156:157]
	v_lshl_add_u64 v[158:159], s[36:37], 0, v[156:157]
	v_lshlrev_b64 v[160:161], 12, v[200:201]
	v_or_b32_e32 v140, 16, v200
	v_lshl_add_u64 v[138:139], v[136:137], 0, s[10:11]
	v_lshl_add_u64 v[188:189], v[158:159], 0, v[160:161]
	v_ashrrev_i32_e32 v141, 31, v140
	v_add_co_u32_e32 v136, vcc, s56, v136
	global_load_dwordx4 v[132:135], v[138:139], off offset:64 nt
	global_load_dwordx4 v[128:131], v[138:139], off offset:512 nt
	global_load_dwordx4 v[168:171], v[188:189], off nt
	global_load_dwordx4 v[172:175], v[188:189], off offset:64 nt
	global_load_dwordx4 v[176:179], v[188:189], off offset:512 nt
	v_lshlrev_b64 v[202:203], 12, v[140:141]
	v_lshl_add_u64 v[196:197], v[158:159], 0, v[202:203]
	v_addc_co_u32_e32 v137, vcc, 0, v137, vcc
	global_load_dwordx4 v[180:183], v[196:197], off offset:64 nt
	global_load_dwordx4 v[184:187], v[196:197], off offset:512 nt
	global_load_dwordx4 v[140:143], v[136:137], off nt
	s_nop 0
	global_load_dwordx4 v[136:139], v[138:139], off offset:576 nt
	s_nop 0
	global_load_dwordx4 v[188:191], v[188:189], off offset:576 nt
	s_nop 0
	global_load_dwordx4 v[192:195], v[196:197], off nt
	s_nop 0
	global_load_dwordx4 v[196:199], v[196:197], off offset:576 nt
	v_lshl_add_u64 v[206:207], s[90:91], 0, v[160:161]
	v_lshl_add_u64 v[206:207], v[206:207], 0, v[156:157]
	v_lshl_add_u64 v[210:211], v[206:207], 0, 64
	v_lshl_add_u64 v[212:213], v[206:207], 0, s[12:13]
	v_lshl_add_u64 v[202:203], s[90:91], 0, v[202:203]
	v_lshl_add_u64 v[214:215], v[206:207], 0, s[14:15]
	v_lshl_add_u64 v[202:203], v[202:203], 0, v[156:157]
	v_or_b32_e32 v204, 32, v200
	v_lshl_add_u64 v[216:217], v[202:203], 0, 64
	v_ashrrev_i32_e32 v205, 31, v204
	v_lshl_add_u64 v[218:219], v[202:203], 0, s[12:13]
	v_lshlrev_b64 v[204:205], 12, v[204:205]
	v_lshl_add_u64 v[220:221], v[202:203], 0, s[14:15]
	v_lshl_add_u64 v[208:209], v[158:159], 0, v[204:205]
	s_andn2_b64 vcc, exec, s[0:1]
	s_mov_b64 s[0:1], -1
	s_waitcnt vmcnt(0)
	v_pk_fma_f32 v[126:127], v[126:127], v[134:135], v[174:175]
	v_pk_fma_f32 v[124:125], v[124:125], v[132:133], v[172:173]
	v_pk_fma_f32 v[110:111], v[110:111], v[130:131], v[178:179]
	v_pk_fma_f32 v[122:123], v[122:123], v[142:143], v[170:171]
	v_pk_fma_f32 v[120:121], v[120:121], v[140:141], v[168:169]
	v_pk_fma_f32 v[108:109], v[108:109], v[128:129], v[176:177]
	global_store_dwordx4 v[206:207], v[120:123], off sc1
	global_store_dwordx4 v[210:211], v[124:127], off sc1
	v_pk_fma_f32 v[106:107], v[106:107], v[138:139], v[190:191]
	global_store_dwordx4 v[212:213], v[108:111], off sc1
	v_pk_fma_f32 v[104:105], v[104:105], v[136:137], v[188:189]
	v_pk_fma_f32 v[114:115], v[114:115], v[142:143], v[194:195]
	global_store_dwordx4 v[214:215], v[104:107], off sc1
	v_pk_fma_f32 v[112:113], v[112:113], v[140:141], v[192:193]
	v_pk_fma_f32 v[118:119], v[118:119], v[134:135], v[182:183]
	global_store_dwordx4 v[202:203], v[112:115], off sc1
	v_pk_fma_f32 v[116:117], v[116:117], v[132:133], v[180:181]
	v_pk_fma_f32 v[102:103], v[102:103], v[130:131], v[186:187]
	global_store_dwordx4 v[216:217], v[116:119], off sc1
	v_pk_fma_f32 v[100:101], v[100:101], v[128:129], v[184:185]
	v_pk_fma_f32 v[98:99], v[98:99], v[138:139], v[198:199]
	global_store_dwordx4 v[218:219], v[100:103], off sc1
	v_pk_fma_f32 v[96:97], v[96:97], v[136:137], v[196:197]
	v_or_b32_e32 v108, 48, v200
	global_store_dwordx4 v[220:221], v[96:99], off sc1
	global_load_dwordx4 v[96:99], v[208:209], off nt
	global_load_dwordx4 v[100:103], v[208:209], off offset:64 nt
	v_ashrrev_i32_e32 v109, 31, v108
	global_load_dwordx4 v[104:107], v[208:209], off offset:512 nt
	v_lshlrev_b64 v[168:169], 12, v[108:109]
	global_load_dwordx4 v[108:111], v[208:209], off offset:576 nt
	v_lshl_add_u64 v[124:125], v[158:159], 0, v[168:169]
	global_load_dwordx4 v[112:115], v[124:125], off nt
	global_load_dwordx4 v[116:119], v[124:125], off offset:64 nt
	global_load_dwordx4 v[120:123], v[124:125], off offset:512 nt
	s_nop 0
	global_load_dwordx4 v[124:127], v[124:125], off offset:576 nt
	v_lshl_add_u64 v[172:173], s[90:91], 0, v[204:205]
	v_lshl_add_u64 v[172:173], v[172:173], 0, v[156:157]
	v_lshl_add_u64 v[176:177], v[172:173], 0, 64
	v_lshl_add_u64 v[178:179], v[172:173], 0, s[12:13]
	v_lshl_add_u64 v[168:169], s[90:91], 0, v[168:169]
	v_lshl_add_u64 v[180:181], v[172:173], 0, s[14:15]
	v_lshl_add_u64 v[168:169], v[168:169], 0, v[156:157]
	v_lshl_add_u64 v[182:183], v[168:169], 0, 64
	v_lshl_add_u64 v[184:185], v[168:169], 0, s[12:13]
	v_lshl_add_u64 v[170:171], v[160:161], 0, s[16:17]
	v_lshl_add_u64 v[186:187], v[168:169], 0, s[14:15]
	v_lshl_add_u64 v[174:175], v[158:159], 0, v[170:171]
	s_waitcnt vmcnt(7)
	v_pk_fma_f32 v[94:95], v[94:95], v[142:143], v[98:99]
	v_pk_fma_f32 v[92:93], v[92:93], v[140:141], v[96:97]
	s_waitcnt vmcnt(6)
	v_pk_fma_f32 v[90:91], v[90:91], v[134:135], v[102:103]
	global_store_dwordx4 v[172:173], v[92:95], off sc1
	v_pk_fma_f32 v[88:89], v[88:89], v[132:133], v[100:101]
	s_waitcnt vmcnt(5)
	v_pk_fma_f32 v[78:79], v[78:79], v[130:131], v[106:107]
	global_store_dwordx4 v[176:177], v[88:91], off sc1
	v_pk_fma_f32 v[76:77], v[76:77], v[128:129], v[104:105]
	s_waitcnt vmcnt(4)
;     __device__ __forceinline__ void operator()(const f32x4 (&acc)[2][2][4][2], const pg8::Unit& u, int wr, int wc, int fr, int fq) const {
;     ...
;             for (int mp = 0; mp < 2; ++mp) {
;                 f32x4 xv[2][2][2];
; #pragma unroll
;                 for (int mm = 0; mm < 2; ++mm) { const float* xr = xp + (size_t)(row0 + ai * 128 + (2 * mp + mm) * 16) * DM + col0;
; #pragma unroll
;                     for (int bj = 0; bj < 2; ++bj)
; #pragma unroll
;                         for (int n = 0; n < 2; ++n) xv[mm][bj][n] = *(const f32x4*)(xr + bj * 128 + 16 * n); }
;                 asm volatile("" ::: "memory");
; #pragma unroll
;                 for (int mm = 0; mm < 2; ++mm) { float* yr = yp + (size_t)(row0 + ai * 128 + (2 * mp + mm) * 16) * DM + col0;
; #pragma unroll
;                     for (int bj = 0; bj < 2; ++bj)
; #pragma unroll
;                         for (int n = 0; n < 2; ++n) { const f32x4 yv = xv[mm][bj][n] + gv[bj][n] * acc[ai][bj][2 * mp + mm][n]; const float* yp_ = yr + bj * 128 + 16 * n;
;                             asm volatile("global_store_dwordx4 %0, %1, off sc1" :: "v"(yp_), "v"(yv) : "memory"); } }
	v_pk_fma_f32 v[74:75], v[74:75], v[138:139], v[110:111]
	global_store_dwordx4 v[178:179], v[76:79], off sc1
	v_pk_fma_f32 v[72:73], v[72:73], v[136:137], v[108:109]
	s_waitcnt vmcnt(3)
	v_pk_fma_f32 v[86:87], v[86:87], v[142:143], v[114:115]
	global_store_dwordx4 v[180:181], v[72:75], off sc1
	v_pk_fma_f32 v[84:85], v[84:85], v[140:141], v[112:113]
	s_waitcnt vmcnt(2)
	v_pk_fma_f32 v[82:83], v[82:83], v[134:135], v[118:119]
	global_store_dwordx4 v[168:169], v[84:87], off sc1
	v_pk_fma_f32 v[80:81], v[80:81], v[132:133], v[116:117]
	s_waitcnt vmcnt(1)
	v_pk_fma_f32 v[70:71], v[70:71], v[130:131], v[122:123]
	global_store_dwordx4 v[182:183], v[80:83], off sc1
	v_pk_fma_f32 v[68:69], v[68:69], v[128:129], v[120:121]
	s_waitcnt vmcnt(0)
	v_pk_fma_f32 v[66:67], v[66:67], v[138:139], v[126:127]
	global_store_dwordx4 v[184:185], v[68:71], off sc1
	v_pk_fma_f32 v[64:65], v[64:65], v[136:137], v[124:125]
	v_lshl_add_u64 v[96:97], v[160:161], 0, s[18:19]
	global_store_dwordx4 v[186:187], v[64:67], off sc1
	global_load_dwordx4 v[64:67], v[174:175], off nt
	global_load_dwordx4 v[68:71], v[174:175], off offset:64 nt
	global_load_dwordx4 v[72:75], v[174:175], off offset:512 nt
	global_load_dwordx4 v[76:79], v[174:175], off offset:576 nt
	v_lshl_add_u64 v[92:93], v[158:159], 0, v[96:97]
	global_load_dwordx4 v[80:83], v[92:93], off nt
	global_load_dwordx4 v[84:87], v[92:93], off offset:64 nt
	global_load_dwordx4 v[88:91], v[92:93], off offset:512 nt
	s_nop 0
	global_load_dwordx4 v[92:95], v[92:93], off offset:576 nt
	v_lshl_add_u64 v[100:101], s[90:91], 0, v[170:171]
	v_lshl_add_u64 v[100:101], v[100:101], 0, v[156:157]
	v_lshl_add_u64 v[104:105], v[100:101], 0, 64
	v_lshl_add_u64 v[106:107], v[100:101], 0, s[12:13]
	v_lshl_add_u64 v[96:97], s[90:91], 0, v[96:97]
	v_lshl_add_u64 v[108:109], v[100:101], 0, s[14:15]
	v_lshl_add_u64 v[96:97], v[96:97], 0, v[156:157]
	v_lshl_add_u64 v[110:111], v[96:97], 0, 64
	v_lshl_add_u64 v[112:113], v[96:97], 0, s[12:13]
	v_lshl_add_u64 v[98:99], v[160:161], 0, s[20:21]
	v_lshl_add_u64 v[114:115], v[96:97], 0, s[14:15]
	v_lshl_add_u64 v[102:103], v[158:159], 0, v[98:99]
	s_waitcnt vmcnt(7)
	v_pk_fma_f32 v[62:63], v[62:63], v[142:143], v[66:67]
	v_pk_fma_f32 v[60:61], v[60:61], v[140:141], v[64:65]
	s_waitcnt vmcnt(6)
	v_pk_fma_f32 v[58:59], v[58:59], v[134:135], v[70:71]
	global_store_dwordx4 v[100:101], v[60:63], off sc1
	v_pk_fma_f32 v[56:57], v[56:57], v[132:133], v[68:69]
	s_waitcnt vmcnt(5)
	v_pk_fma_f32 v[46:47], v[46:47], v[130:131], v[74:75]
	global_store_dwordx4 v[104:105], v[56:59], off sc1
	v_pk_fma_f32 v[44:45], v[44:45], v[128:129], v[72:73]
	s_waitcnt vmcnt(4)
	v_pk_fma_f32 v[42:43], v[42:43], v[138:139], v[78:79]
	global_store_dwordx4 v[106:107], v[44:47], off sc1
	v_pk_fma_f32 v[40:41], v[40:41], v[136:137], v[76:77]
	s_waitcnt vmcnt(3)
	v_pk_fma_f32 v[54:55], v[54:55], v[142:143], v[82:83]
	global_store_dwordx4 v[108:109], v[40:43], off sc1
	v_pk_fma_f32 v[52:53], v[52:53], v[140:141], v[80:81]
	s_waitcnt vmcnt(2)
	v_pk_fma_f32 v[50:51], v[50:51], v[134:135], v[86:87]
	global_store_dwordx4 v[96:97], v[52:55], off sc1
	v_pk_fma_f32 v[48:49], v[48:49], v[132:133], v[84:85]
	s_waitcnt vmcnt(1)
	v_pk_fma_f32 v[38:39], v[38:39], v[130:131], v[90:91]
	global_store_dwordx4 v[110:111], v[48:51], off sc1
	v_pk_fma_f32 v[36:37], v[36:37], v[128:129], v[88:89]
	s_waitcnt vmcnt(0)
	v_pk_fma_f32 v[34:35], v[34:35], v[138:139], v[94:95]
	global_store_dwordx4 v[112:113], v[36:39], off sc1
	v_pk_fma_f32 v[32:33], v[32:33], v[136:137], v[92:93]
	v_lshl_add_u64 v[64:65], v[160:161], 0, s[22:23]
	global_store_dwordx4 v[114:115], v[32:35], off sc1
	global_load_dwordx4 v[32:35], v[102:103], off nt
	global_load_dwordx4 v[36:39], v[102:103], off offset:64 nt
	global_load_dwordx4 v[40:43], v[102:103], off offset:512 nt
	global_load_dwordx4 v[44:47], v[102:103], off offset:576 nt
	v_lshl_add_u64 v[60:61], v[158:159], 0, v[64:65]
	global_load_dwordx4 v[48:51], v[60:61], off nt
	global_load_dwordx4 v[52:55], v[60:61], off offset:64 nt
	global_load_dwordx4 v[56:59], v[60:61], off offset:512 nt
	s_nop 0
	global_load_dwordx4 v[60:63], v[60:61], off offset:576 nt
	v_lshl_add_u64 v[66:67], s[90:91], 0, v[98:99]
	v_lshl_add_u64 v[66:67], v[66:67], 0, v[156:157]
	v_lshl_add_u64 v[68:69], v[66:67], 0, 64
	v_lshl_add_u64 v[70:71], v[66:67], 0, s[12:13]
	v_lshl_add_u64 v[64:65], s[90:91], 0, v[64:65]
	v_lshl_add_u64 v[72:73], v[66:67], 0, s[14:15]
	v_lshl_add_u64 v[64:65], v[64:65], 0, v[156:157]
	v_lshl_add_u64 v[74:75], v[64:65], 0, 64
	v_lshl_add_u64 v[76:77], v[64:65], 0, s[12:13]
	v_lshl_add_u64 v[78:79], v[64:65], 0, s[14:15]
	s_waitcnt vmcnt(7)
	v_pk_fma_f32 v[30:31], v[30:31], v[142:143], v[34:35]
	v_pk_fma_f32 v[28:29], v[28:29], v[140:141], v[32:33]
	s_waitcnt vmcnt(6)
	v_pk_fma_f32 v[26:27], v[26:27], v[134:135], v[38:39]
	global_store_dwordx4 v[66:67], v[28:31], off sc1
	v_pk_fma_f32 v[24:25], v[24:25], v[132:133], v[36:37]
	s_waitcnt vmcnt(5)
	v_pk_fma_f32 v[14:15], v[14:15], v[130:131], v[42:43]
	global_store_dwordx4 v[68:69], v[24:27], off sc1
	v_pk_fma_f32 v[12:13], v[12:13], v[128:129], v[40:41]
	s_waitcnt vmcnt(4)
	v_pk_fma_f32 v[10:11], v[10:11], v[138:139], v[46:47]
	global_store_dwordx4 v[70:71], v[12:15], off sc1
	v_pk_fma_f32 v[8:9], v[8:9], v[136:137], v[44:45]
	s_waitcnt vmcnt(3)
	v_pk_fma_f32 v[22:23], v[22:23], v[142:143], v[50:51]
	global_store_dwordx4 v[72:73], v[8:11], off sc1
	v_pk_fma_f32 v[20:21], v[20:21], v[140:141], v[48:49]
	s_waitcnt vmcnt(2)
	v_pk_fma_f32 v[18:19], v[18:19], v[134:135], v[54:55]
	global_store_dwordx4 v[64:65], v[20:23], off sc1
	v_pk_fma_f32 v[16:17], v[16:17], v[132:133], v[52:53]
	s_waitcnt vmcnt(1)
	v_pk_fma_f32 v[6:7], v[6:7], v[130:131], v[58:59]
	global_store_dwordx4 v[74:75], v[16:19], off sc1
	v_pk_fma_f32 v[4:5], v[4:5], v[128:129], v[56:57]
	s_waitcnt vmcnt(0)
	v_pk_fma_f32 v[2:3], v[2:3], v[138:139], v[62:63]
	global_store_dwordx4 v[76:77], v[4:7], off sc1
	v_pk_fma_f32 v[0:1], v[0:1], v[136:137], v[60:61]
	s_nop 0
	global_store_dwordx4 v[78:79], v[0:3], off sc1
	s_cbranch_vccnz .LBB0_1039
	s_andn2_b64 vcc, exec, s[4:5]
	s_cbranch_vccnz .LBB0_1038
	s_barrier
	s_branch .LBB0_1038
